# deferred weight conversion, 14 tiles per idle wave (4704 w_down tiles out of phase 0 into the gate-up phase's last-round idle workgroups; tail fits the idle window by probe)
# baseline (speedup 1.0000x reference)
.LBB0_9:
	s_add_i32 s94, s94, s18
	s_add_i32 s19, s19, s80
	s_add_i32 s82, s82, s83
	s_cmp_lt_u32 s94, 0x9ea0
	s_cbranch_scc1 .Ldf_nohole
	s_cmp_gt_u32 s94, 0xb0ff
	s_cbranch_scc1 .Ldf_nohole
	s_add_i32 s94, s94, 0x1260
	s_add_i32 s19, s19, 0x49800
	s_add_i32 s82, s82, 0x9300
	v_add_u32_e32 v85, 0x126000, v85

.LBB0_695:
	v_readfirstlane_b32 s87, v226
	s_lshr_b32 s87, s87, 6
	s_cmp_eq_u32 s78, 0x100
	s_cbranch_scc1 .Ldf_g256
	s_lshl_b32 s88, s2, 3
	s_lshl_b32 s84, s78, 3
	s_branch .Ldf_go
.Ldf_g256:
	s_cmp_lt_u32 s2, 214
	s_cbranch_scc1 .Ldf_done
	s_sub_i32 s88, s2, 214
	s_lshl_b32 s88, s88, 3
	s_movk_i32 s84, 336
.Ldf_go:
	s_add_i32 s88, s88, s87
	s_add_i32 s85, s88, 0x9ea0
	v_readlane_b32 s90, v254, 10
	v_readlane_b32 s91, v254, 11
	s_mov_b64 s[80:81], 0x80
	s_mov_b64 s[82:83], 0xc0
	v_and_b32_e32 v1, 63, v226
	v_lshlrev_b32_e32 v66, 4, v1
	v_lshlrev_b32_e32 v3, 6, v1
	v_and_b32_e32 v70, 0x180, v3
	v_lshlrev_b32_e32 v2, 2, v1
	v_and_b32_e32 v71, 28, v2
	v_and_b32_e32 v2, 24, v226
	v_mov_b32_e32 v69, 0
	v_lshlrev_b32_e32 v68, 1, v70
	v_lshl_add_u64 v[76:77], s[26:27], 0, v[68:69]
	v_lshlrev_b32_e32 v4, 1, v2
	v_mov_b32_e32 v5, v69
	v_lshl_add_u64 v[78:79], v[76:77], 0, v[4:5]
	v_and_b32_e32 v67, 56, v226
	v_and_b32_e32 v84, 16, v66
	v_lshlrev_b32_e32 v68, 1, v2
.Ldf_loop:
	s_lshl_b32 s86, s85, 6
	s_add_i32 s87, s85, 0x7a00
	s_and_b32 s87, s87, 0xffc0
	v_or_b32_e32 v88, s87, v67
	s_and_b32 s87, s86, 0xfc0
	v_or_b32_e32 v2, s87, v71
	v_lshlrev_b32_e32 v2, 2, v2
	v_mov_b32_e32 v3, v69
	v_lshlrev_b32_e32 v30, 14, v88
	v_lshl_add_u64 v[34:35], s[90:91], 0, v[2:3]
	v_mov_b32_e32 v31, v69
	v_or_b32_e32 v38, 0x4000, v30
	v_mov_b32_e32 v39, v69
	v_or_b32_e32 v42, 0x8000, v30
	v_mov_b32_e32 v43, v69
	v_or_b32_e32 v44, 0xc000, v30
	v_mov_b32_e32 v45, v69
	v_or_b32_e32 v50, 0x10000, v30
	v_mov_b32_e32 v51, v69
	v_or_b32_e32 v52, 0x14000, v30
	v_mov_b32_e32 v53, v69
	v_or_b32_e32 v58, 0x18000, v30
	v_mov_b32_e32 v59, v69
	v_lshl_add_u64 v[36:37], v[34:35], 0, v[30:31]
	v_lshl_add_u64 v[6:7], v[34:35], 0, v[38:39]
	v_lshl_add_u64 v[10:11], v[34:35], 0, v[42:43]
	v_lshl_add_u64 v[14:15], v[34:35], 0, v[44:45]
	v_lshl_add_u64 v[18:19], v[34:35], 0, v[50:51]
	v_lshl_add_u64 v[22:23], v[34:35], 0, v[52:53]
	v_lshl_add_u64 v[26:27], v[34:35], 0, v[58:59]
	global_load_dwordx4 v[2:5], v[36:37], off
	s_nop 0
	global_load_dwordx4 v[6:9], v[6:7], off
	s_nop 0
	global_load_dwordx4 v[10:13], v[10:11], off
	s_nop 0
	global_load_dwordx4 v[14:17], v[14:15], off
	s_nop 0
	global_load_dwordx4 v[18:21], v[18:19], off
	s_nop 0
	global_load_dwordx4 v[22:25], v[22:23], off
	s_nop 0
	global_load_dwordx4 v[26:29], v[26:27], off
	v_or_b32_e32 v60, 0x1c000, v30
	v_mov_b32_e32 v61, v69
	v_lshl_add_u64 v[62:63], v[34:35], 0, s[80:81]
	v_lshl_add_u64 v[30:31], v[34:35], 0, v[60:61]
	v_lshl_add_u64 v[38:39], v[62:63], 0, v[38:39]
	v_lshl_add_u64 v[42:43], v[62:63], 0, v[42:43]
	v_lshl_add_u64 v[46:47], v[62:63], 0, v[44:45]
	v_lshl_add_u64 v[50:51], v[62:63], 0, v[50:51]
	v_lshl_add_u64 v[54:55], v[62:63], 0, v[52:53]
	v_lshl_add_u64 v[58:59], v[62:63], 0, v[58:59]
	v_lshl_add_u64 v[62:63], v[62:63], 0, v[60:61]
	global_load_dwordx4 v[30:33], v[30:31], off
	v_or_b32_e32 v90, s87, v84
	global_load_dwordx4 v[34:37], v[36:37], off offset:128
	v_lshrrev_b32_e32 v90, 4, v90
	global_load_dwordx4 v[38:41], v[38:39], off
	s_nop 0
	global_load_dwordx4 v[42:45], v[42:43], off
	s_nop 0
	global_load_dwordx4 v[46:49], v[46:47], off
	s_nop 0
	global_load_dwordx4 v[50:53], v[50:51], off
	s_nop 0
	global_load_dwordx4 v[54:57], v[54:55], off
	s_nop 0
	global_load_dwordx4 v[58:61], v[58:59], off
	s_nop 0
	global_load_dwordx4 v[62:65], v[62:63], off
	v_lshrrev_b32_e32 v88, 5, v88
	v_mul_u32_u24_e32 v90, 0x158, v90
	v_mov_b32_e32 v89, v69
	v_add_lshl_u32 v88, v90, v88, 10
	v_lshl_add_u64 v[96:97], v[78:79], 0, v[88:89]
	v_add_u32_e32 v92, 0xac000, v88
	v_mov_b32_e32 v93, v69
	v_lshl_add_u64 v[98:99], v[78:79], 0, v[92:93]
	s_waitcnt vmcnt(14)
	v_cvt_pk_bf16_f32 v88, v2, v6
	s_waitcnt vmcnt(12)
	v_cvt_pk_bf16_f32 v89, v10, v14
	s_waitcnt vmcnt(10)
	v_cvt_pk_bf16_f32 v90, v18, v22
	s_waitcnt vmcnt(8)
	v_cvt_pk_bf16_f32 v91, v26, v30
	global_store_dwordx4 v[96:97], v[88:91], off
	s_nop 1
	v_cvt_pk_bf16_f32 v88, v3, v7
	v_cvt_pk_bf16_f32 v89, v11, v15
	v_cvt_pk_bf16_f32 v90, v19, v23
	v_cvt_pk_bf16_f32 v91, v27, v31
	global_store_dwordx4 v[96:97], v[88:91], off offset:64
	v_lshl_add_u64 v[6:7], v[76:77], 0, v[92:93]
	s_nop 0
	v_cvt_pk_bf16_f32 v88, v4, v8
	v_cvt_pk_bf16_f32 v89, v12, v16
	v_cvt_pk_bf16_f32 v90, v20, v24
	v_cvt_pk_bf16_f32 v91, v28, v32
	global_store_dwordx4 v[96:97], v[88:91], off offset:128
	v_cvt_pk_bf16_f32 v2, v5, v9
	v_cvt_pk_bf16_f32 v3, v13, v17
	v_cvt_pk_bf16_f32 v4, v21, v25
	v_cvt_pk_bf16_f32 v5, v29, v33
	global_store_dwordx4 v[96:97], v[2:5], off offset:192
	v_lshl_add_u64 v[8:9], v[6:7], 0, v[68:69]
	v_lshl_add_u64 v[6:7], v[6:7], 0, s[82:83]
	s_waitcnt vmcnt(10)
	v_cvt_pk_bf16_f32 v2, v34, v38
	s_waitcnt vmcnt(8)
	v_cvt_pk_bf16_f32 v3, v42, v46
	s_waitcnt vmcnt(6)
	v_cvt_pk_bf16_f32 v4, v50, v54
	s_waitcnt vmcnt(4)
	v_cvt_pk_bf16_f32 v5, v58, v62
	global_store_dwordx4 v[98:99], v[2:5], off
	s_nop 1
	v_cvt_pk_bf16_f32 v2, v35, v39
	v_cvt_pk_bf16_f32 v3, v43, v47
	v_cvt_pk_bf16_f32 v4, v51, v55
	v_cvt_pk_bf16_f32 v5, v59, v63
	global_store_dwordx4 v[8:9], v[2:5], off offset:64
	s_nop 1
	v_cvt_pk_bf16_f32 v2, v36, v40
	v_cvt_pk_bf16_f32 v3, v44, v48
	v_cvt_pk_bf16_f32 v4, v52, v56
	v_cvt_pk_bf16_f32 v5, v60, v64
	global_store_dwordx4 v[8:9], v[2:5], off offset:128
	s_nop 1
	v_cvt_pk_bf16_f32 v2, v37, v41
	v_cvt_pk_bf16_f32 v3, v45, v49
	v_cvt_pk_bf16_f32 v4, v53, v57
	v_cvt_pk_bf16_f32 v5, v61, v65
	v_lshl_add_u64 v[6:7], v[6:7], 0, v[68:69]
	global_store_dwordx4 v[6:7], v[2:5], off
	s_add_i32 s85, s85, s84
	s_cmp_gt_u32 s85, 0xb0ff
	s_cbranch_scc0 .Ldf_loop
